# P0: first row step's loads issued one table-build stage earlier (D-term load first, its consumer waits with vmcnt(16))
# speedup vs baseline: 1.0004x; 1.0004x over previous
; #define INP(k) ((const float*)(GAS const float*)KARG64(8 * (k)))
; #define R1 ((float*)(WSP() + WS_R1))
; __device__ __forceinline__ void ssm_tables(int g, int part, LAS float* L, bf16* __restrict__ TE, bf16* __restrict__ FT, float* __restrict__ LAM16) {
;     ...
;     for (int i = tid; i < 1024; i += 512) {
;         const int p = i >> 4; const float br = INP(7)[g * 1024 + i], bi = INP(8)[g * 1024 + i];
;         Bbr[i] = fr_[p] * br - fi_[p] * bi; Bbi[i] = fr_[p] * bi + fi_[p] * br;
;         Cr[i] = INP(9)[g * 1024 + i]; Ci[i] = INP(10)[g * 1024 + i];
;     }
;     __syncthreads();
;     {
;         const int k = tid >> 5, cl = (tid >> 4) & 1, c = 2 * part + cl, c2 = tid & 15; float s = 0.f;
;         for (int p = 0; p < 64; ++p) {
;             const float cr = Cr[c * 64 + p], ci = Ci[c * 64 + p], lr = lkr[k * 64 + p], li = lki[k * 64 + p];
;             const float xr = cr * lr - ci * li, xi = cr * li + ci * lr;
;             s += xr * Bbr[p * 16 + c2] - xi * Bbi[p * 16 + c2];
;         }
;         if (k == 0 && c == c2) s += INP(11)[g * 16 + c];
;         Kt[tid] = s;
; __global__ void __launch_bounds__(NWAVES * 64, 2) hybrid_fwd(Params P) {
;     ...
;         for (int m0 = gw * 4; m0 < MAINR + NMETA; m0 += NGW * 4) {
;             const float* src[4]; bf16* dst[4]; float* rr[4];
; #pragma unroll
;             for (int r = 0; r < 4; ++r) { const int m = m0 + r; src[r] = m < MAINR ? INP(0) + (size_t)m * 1024 : INP(1) + (size_t)(m - MAINR) * 1024; dst[r] = XB + (size_t)m * 1024; rr[r] = R1 + m; }
;             rows_to_bf16<4>(src, dst, rr, lane);
.LBB0_13:
	s_mov_b64 s[18:19], s[0:1]
	s_load_dwordx2 s[18:19], s[18:19], 0x38
	v_add_u32_e32 v6, s13, v5
	v_ashrrev_i32_e32 v7, 31, v6
	v_lshlrev_b64 v[6:7], 2, v[6:7]
	s_mov_b64 s[20:21], s[0:1]
	s_waitcnt lgkmcnt(0)
	v_lshl_add_u64 v[22:23], s[18:19], 0, v[6:7]
	global_load_dword v24, v[22:23], off
	s_load_dwordx2 s[18:19], s[20:21], 0x40
	v_cmp_lt_u32_e32 vcc, s23, v5
	s_or_b64 s[16:17], vcc, s[16:17]
	s_waitcnt lgkmcnt(0)
	v_lshl_add_u64 v[22:23], s[18:19], 0, v[6:7]
	global_load_dword v22, v[22:23], off
	ds_read_b32 v23, v2 offset:256
	ds_read_b32 v25, v2
	s_mov_b64 s[18:19], s[0:1]
	s_waitcnt vmcnt(0) lgkmcnt(1)
	v_mul_f32_e32 v23, v22, v23
	s_waitcnt lgkmcnt(0)
	v_fma_f32 v23, v24, v25, -v23
	ds_write_b32 v4, v23
	ds_read_b32 v23, v2 offset:256
	ds_read_b32 v25, v2
	v_add_u32_e32 v2, 0x80, v2
	s_waitcnt lgkmcnt(1)
	v_mul_f32_e32 v23, v24, v23
	s_waitcnt lgkmcnt(0)
	v_fmac_f32_e32 v23, v22, v25
	ds_write_b32 v4, v23 offset:4096
	s_load_dwordx2 s[18:19], s[18:19], 0x48
	s_waitcnt lgkmcnt(0)
	v_lshl_add_u64 v[22:23], s[18:19], 0, v[6:7]
	global_load_dword v22, v[22:23], off
	s_mov_b64 s[18:19], s[0:1]
	s_waitcnt vmcnt(0)
	ds_write_b32 v4, v22 offset:8192
	s_load_dwordx2 s[18:19], s[18:19], 0x50
	s_waitcnt lgkmcnt(0)
	v_lshl_add_u64 v[6:7], s[18:19], 0, v[6:7]
	global_load_dword v6, v[6:7], off
	v_add_u32_e32 v7, 0x200, v5
	v_mov_b32_e32 v5, v7
	s_waitcnt vmcnt(0)
	ds_write_b32 v4, v6 offset:12288
	v_add_u32_e32 v4, 0x800, v4
	s_andn2_b64 exec, exec, s[16:17]
	s_cbranch_execnz .LBB0_13
	s_or_b64 exec, exec, s[16:17]
	s_and_b32 s13, s31, 7
	v_lshl_add_u32 v4, s13, 9, v16
	v_mov_b32_e32 v2, 0
	s_mov_b32 s13, 0
	v_mov_b32_e32 v5, v15
	s_waitcnt lgkmcnt(0)
	s_barrier
	s_mov_b64 s[68:69], exec
	s_mov_b64 exec, -1
	s_load_dwordx2 s[70:71], s[0:1], 0x58
	s_load_dwordx2 s[60:61], s[0:1], 0x0
	v_lshl_or_b32 v92, s12, 4, v10
	v_ashrrev_i32_e32 v93, 31, v92
	v_lshlrev_b32_e32 v91, 4, v174
	s_lshl_b32 s62, s57, 14
	s_waitcnt lgkmcnt(0)
	v_lshl_add_u64 v[92:93], v[92:93], 2, s[70:71]
	s_add_u32 s60, s60, s62
	s_addc_u32 s61, s61, 0
	s_add_u32 s62, s60, 0x1000
	s_addc_u32 s63, s61, 0
	s_add_u32 s64, s60, 0x2000
	s_addc_u32 s65, s61, 0
	s_add_u32 s66, s60, 0x3000
	s_addc_u32 s67, s61, 0
	global_load_dword v92, v[92:93], off
	global_load_dwordx4 v[160:163], v91, s[60:61] nt
	global_load_dwordx4 v[156:159], v91, s[60:61] offset:1024 nt
	global_load_dwordx4 v[152:155], v91, s[60:61] offset:2048 nt
	global_load_dwordx4 v[148:151], v91, s[60:61] offset:3072 nt
	global_load_dwordx4 v[144:147], v91, s[62:63] nt
	global_load_dwordx4 v[140:143], v91, s[62:63] offset:1024 nt
	global_load_dwordx4 v[136:139], v91, s[62:63] offset:2048 nt
	global_load_dwordx4 v[132:135], v91, s[62:63] offset:3072 nt
	global_load_dwordx4 v[128:131], v91, s[64:65] nt
	global_load_dwordx4 v[124:127], v91, s[64:65] offset:1024 nt
	global_load_dwordx4 v[120:123], v91, s[64:65] offset:2048 nt
	global_load_dwordx4 v[116:119], v91, s[64:65] offset:3072 nt
	global_load_dwordx4 v[112:115], v91, s[66:67] nt
	global_load_dwordx4 v[108:111], v91, s[66:67] offset:1024 nt
	global_load_dwordx4 v[104:107], v91, s[66:67] offset:2048 nt
	global_load_dwordx4 v[100:103], v91, s[66:67] offset:3072 nt
	s_mov_b32 s59, 1
	s_mov_b64 exec, s[68:69]
.LBB0_15:
	v_add_u32_e32 v26, s13, v4
	v_add_u32_e32 v34, s13, v14
	v_add_u32_e32 v42, 0x1000, v5
	ds_read2_b32 v[6:7], v5 offset1:16
	ds_read2_b32 v[38:39], v5 offset0:32 offset1:48
	ds_read_b128 v[22:25], v26
	ds_read_b128 v[26:29], v26 offset:4096
	ds_read_b128 v[30:33], v34
	ds_read_b128 v[34:37], v34 offset:4352
	ds_read2_b32 v[40:41], v42 offset1:16
	ds_read2_b32 v[42:43], v42 offset0:32 offset1:48
	s_waitcnt lgkmcnt(4)
	v_mov_b32_e32 v46, v26
	v_mov_b32_e32 v47, v22
	v_mov_b32_e32 v22, v27
	s_waitcnt lgkmcnt(2)
	v_pk_mul_f32 v[52:53], v[46:47], v[34:35] op_sel_hi:[1,0]
	v_mov_b32_e32 v26, v31
	v_mov_b32_e32 v48, v28
	v_mov_b32_e32 v49, v24
	v_mov_b32_e32 v24, v29
	v_mov_b32_e32 v28, v37
	v_pk_mul_f32 v[34:35], v[22:23], v[34:35] op_sel:[0,1]
	v_pk_fma_f32 v[54:55], v[46:47], v[30:31], v[52:53] op_sel:[1,0,0] op_sel_hi:[0,1,1] neg_lo:[0,0,1] neg_hi:[0,0,1]
	v_pk_fma_f32 v[46:47], v[46:47], v[30:31], v[52:53] op_sel:[1,0,0] op_sel_hi:[0,0,1]
	v_mov_b32_e32 v44, v6
	v_mov_b32_e32 v6, v38
	s_waitcnt lgkmcnt(1)
	v_mov_b32_e32 v45, v40
	v_mov_b32_e32 v38, v33
	v_mov_b32_e32 v50, v33
	v_pk_mul_f32 v[36:37], v[48:49], v[36:37] op_sel_hi:[1,0]
	v_pk_mul_f32 v[28:29], v[24:25], v[28:29] op_sel_hi:[1,0]
	v_pk_fma_f32 v[26:27], v[22:23], v[26:27], v[34:35] op_sel:[1,0,0] op_sel_hi:[0,1,1] neg_lo:[0,0,1] neg_hi:[0,0,1]
	v_pk_fma_f32 v[22:23], v[22:23], v[30:31], v[34:35] op_sel:[1,1,0] op_sel_hi:[0,1,1]
	v_mov_b32_e32 v55, v47
	v_mov_b32_e32 v40, v7
	v_pk_fma_f32 v[30:31], v[48:49], v[32:33], v[36:37] op_sel:[1,0,0] op_sel_hi:[0,1,1] neg_lo:[0,0,1] neg_hi:[0,0,1]
	v_pk_fma_f32 v[32:33], v[48:49], v[32:33], v[36:37] op_sel:[1,0,0] op_sel_hi:[0,0,1]
	v_pk_fma_f32 v[34:35], v[24:25], v[38:39], v[28:29] op_sel:[1,0,0] op_sel_hi:[0,1,1] neg_lo:[0,0,1] neg_hi:[0,0,1]
	v_pk_fma_f32 v[24:25], v[24:25], v[50:51], v[28:29] op_sel:[1,0,0] op_sel_hi:[0,0,1]
	v_mov_b32_e32 v27, v23
	v_pk_mul_f32 v[22:23], v[44:45], v[54:55]
	s_waitcnt lgkmcnt(0)
	v_mov_b32_e32 v7, v42
	v_mov_b32_e32 v31, v33
	v_mov_b32_e32 v35, v25
	v_pk_mul_f32 v[24:25], v[40:41], v[26:27]
	v_sub_f32_e32 v22, v22, v23
	v_mov_b32_e32 v42, v39
	v_pk_mul_f32 v[6:7], v[6:7], v[30:31]
	v_sub_f32_e32 v23, v24, v25
	v_add_f32_e32 v2, v2, v22
	v_pk_mul_f32 v[26:27], v[42:43], v[34:35]
	v_sub_f32_e32 v6, v6, v7
	v_add_f32_e32 v2, v2, v23
	s_add_i32 s13, s13, 16
	v_sub_f32_e32 v7, v26, v27
	v_add_f32_e32 v2, v2, v6
	v_add_u32_e32 v5, 0x100, v5
	s_cmpk_eq_i32 s13, 0x100
	v_add_f32_e32 v2, v2, v7
	s_cbranch_scc0 .LBB0_15
	s_lshl_b32 s36, s34, 1
	v_or_b32_e32 v4, s36, v9
	v_cmp_eq_u32_e32 vcc, v4, v10
	s_and_b64 s[18:19], s[6:7], vcc
	s_and_saveexec_b64 s[16:17], s[18:19]
	s_cbranch_execz .LBB0_18
	s_mov_b64 s[18:19], s[0:1]
	s_waitcnt vmcnt(16)
	v_add_f32_e32 v2, v2, v92
